# w_in layer-1 conversion split: 2462 tiles stay in the out GEMM tail of layer 0, the other 930 go to the 80 idle workgroups of the up GEMM last round of layer 0
# baseline (speedup 1.0000x reference)
; #define LAS __attribute__((address_space(3)))
; __device__ __forceinline__ void lds_barrier() { asm volatile("s_waitcnt lgkmcnt(0)" ::: "memory"); __builtin_amdgcn_s_barrier(); asm volatile("" ::: "memory"); }
; __device__ __forceinline__ void convert_weight(int wv, const float* __restrict__ src, int ldsrc, int Ksrc, bf16_t* dst, int ldd, int koff, int ntn, const float* kscale, int mode, LAS float* tile, int pidx, int pcnt) {
;     ...
;     auto prefetch = [&](int t) {
;         const int tn = t % ntn, tk = t / ntn; const int n0 = tn * 64, k0 = tk * 128;
;         int scol = n0, nvalid = 64;
;         if (mode == 1) { if (n0 < 5632) scol = n0; else if (n0 < 13312) scol = n0 + 8; else if (n0 == 13312) { scol = 5632; nvalid = 8; } else { scol = 0; nvalid = 0; } }
; #pragma unroll
;         for (int i = 0; i < 4; ++i) { const int kk = kk0 + i * 32; v[i] = (f32x4){0.f, 0.f, 0.f, 0.f};
;             if (n4 < nvalid) v[i] = *(const f32x4*)(src + (size_t)(k0 + kk) * ldsrc + scol + n4);
;             ks[i] = kscale ? kscale[k0 + kk] : 1.0f; }
;     };
;     int t = pidx; int buf = 0;
;     if (t < total) prefetch(t);
;     for (; t < total; t += G) {
;         LAS float* tl = tile + buf * (128 * 65);
; #pragma unroll
;         for (int i = 0; i < 4; ++i) { const int kk = kk0 + i * 32;
;             tl[kk * 65 + n4 + 0] = v[i][0] * ks[i]; tl[kk * 65 + n4 + 1] = v[i][1] * ks[i]; tl[kk * 65 + n4 + 2] = v[i][2] * ks[i]; tl[kk * 65 + n4 + 3] = v[i][3] * ks[i]; }
;         lds_barrier();
;         const int tn = t % ntn, tk = t / ntn; const int n0 = tn * 64, k0 = tk * 128;
;         if (t + G < total) prefetch(t + G);
.Lcv1_cp0:
	s_mul_i32 s19, s15, 0x1a0400
	s_add_u32 s19, s19, s18
	s_lshl_b32 s19, s19, 2
	s_add_u32 s20, s4, s19
	s_addc_u32 s21, s5, 0
	s_lshl_b32 s19, s15, 9
	s_add_u32 s22, s6, s19
	s_addc_u32 s23, s7, 0
	global_load_dwordx4 v[12:15], v4, s[20:21]
	global_load_dword v28, v5, s[22:23]
	s_add_u32 s20, s20, 0x1a0400
	s_addc_u32 s21, s21, 0
	global_load_dwordx4 v[16:19], v4, s[20:21]
	global_load_dword v29, v5, s[22:23] offset:128
	s_add_u32 s20, s20, 0x1a0400
	s_addc_u32 s21, s21, 0
	global_load_dwordx4 v[20:23], v4, s[20:21]
	global_load_dword v30, v5, s[22:23] offset:256
	s_add_u32 s20, s20, 0x1a0400
	s_addc_u32 s21, s21, 0
	global_load_dwordx4 v[24:27], v4, s[20:21]
	global_load_dword v31, v5, s[22:23] offset:384
	s_add_u32 s11, s10, 192
	s_cmp_lt_u32 s11, 2462
	s_cbranch_scc0 .Lcv1_p1n
	s_mul_hi_u32 s15, s11, 0x13521d0
	s_mul_i32 s14, s15, 212
	s_sub_u32 s14, s11, s14
	s_lshl_b32 s18, s14, 6
	s_mov_b32 s29, 0
	s_cmp_lt_u32 s14, 88
	s_cbranch_scc1 .Lcv1_cp1
	s_add_u32 s18, s18, 8
	s_cmp_lt_u32 s14, 208
	s_cbranch_scc1 .Lcv1_cp1
	s_movk_i32 s18, 0x1600
	s_mov_b32 s29, 1
	s_cmp_eq_u32 s14, 208
	s_cbranch_scc1 .Lcv1_cp1
	s_mov_b32 s18, 0
	s_mov_b32 s29, 2

; #define LAS __attribute__((address_space(3)))
; __device__ __forceinline__ void lds_barrier() { asm volatile("s_waitcnt lgkmcnt(0)" ::: "memory"); __builtin_amdgcn_s_barrier(); asm volatile("" ::: "memory"); }
; __device__ __forceinline__ void convert_weight(int wv, const float* __restrict__ src, int ldsrc, int Ksrc, bf16_t* dst, int ldd, int koff, int ntn, const float* kscale, int mode, LAS float* tile, int pidx, int pcnt) {
;     ...
;         for (int i = 0; i < 4; ++i) { const int kk = kk0 + i * 32; v[i] = (f32x4){0.f, 0.f, 0.f, 0.f};
;             if (n4 < nvalid) v[i] = *(const f32x4*)(src + (size_t)(k0 + kk) * ldsrc + scol + n4);
;             ks[i] = kscale ? kscale[k0 + kk] : 1.0f; }
;     };
;     int t = pidx; int buf = 0;
;     if (t < total) prefetch(t);
;     for (; t < total; t += G) {
;         LAS float* tl = tile + buf * (128 * 65);
; #pragma unroll
;         for (int i = 0; i < 4; ++i) { const int kk = kk0 + i * 32;
;             tl[kk * 65 + n4 + 0] = v[i][0] * ks[i]; tl[kk * 65 + n4 + 1] = v[i][1] * ks[i]; tl[kk * 65 + n4 + 2] = v[i][2] * ks[i]; tl[kk * 65 + n4 + 3] = v[i][3] * ks[i]; }
;         lds_barrier();
;         const int tn = t % ntn, tk = t / ntn; const int n0 = tn * 64, k0 = tk * 128;
;         if (t + G < total) prefetch(t + G);
.Lcv1_ma:
	v_mul_f32_e32 v12, v12, v28
	v_mul_f32_e32 v13, v13, v28
	v_mul_f32_e32 v14, v14, v28
	v_mul_f32_e32 v15, v15, v28
	v_mul_f32_e32 v16, v16, v29
	v_mul_f32_e32 v17, v17, v29
	v_mul_f32_e32 v18, v18, v29
	v_mul_f32_e32 v19, v19, v29
	v_mul_f32_e32 v20, v20, v30
	v_mul_f32_e32 v21, v21, v30
	v_mul_f32_e32 v22, v22, v30
	v_mul_f32_e32 v23, v23, v30
	v_mul_f32_e32 v24, v24, v31
	v_mul_f32_e32 v25, v25, v31
	v_mul_f32_e32 v26, v26, v31
	v_mul_f32_e32 v27, v27, v31
	ds_write_b32 v6, v12 offset:0
	ds_write_b32 v6, v13 offset:4
	ds_write_b32 v6, v14 offset:8
	ds_write_b32 v6, v15 offset:12
	ds_write_b32 v6, v16 offset:8320
	ds_write_b32 v6, v17 offset:8324
	ds_write_b32 v6, v18 offset:8328
	ds_write_b32 v6, v19 offset:8332
	ds_write_b32 v6, v20 offset:16640
	ds_write_b32 v6, v21 offset:16644
	ds_write_b32 v6, v22 offset:16648
	ds_write_b32 v6, v23 offset:16652
	ds_write_b32 v6, v24 offset:24960
	ds_write_b32 v6, v25 offset:24964
	ds_write_b32 v6, v26 offset:24968
	ds_write_b32 v6, v27 offset:24972
	s_waitcnt lgkmcnt(0)
	s_barrier
	s_add_u32 s11, s10, 384
	s_mov_b32 s27, 0
	s_cmp_lt_u32 s11, 2462
	s_cbranch_scc0 .Lcv1_na
	s_mov_b32 s27, 1
	s_mul_hi_u32 s15, s11, 0x13521d0
	s_mul_i32 s14, s15, 212
	s_sub_u32 s14, s11, s14
	s_lshl_b32 s18, s14, 6
	s_mov_b32 s28, 0
	s_cmp_lt_u32 s14, 88
	s_cbranch_scc1 .Lcv1_ca
	s_add_u32 s18, s18, 8
	s_cmp_lt_u32 s14, 208
	s_cbranch_scc1 .Lcv1_ca
	s_movk_i32 s18, 0x1600
	s_mov_b32 s28, 1
	s_cmp_eq_u32 s14, 208
	s_cbranch_scc1 .Lcv1_ca
	s_mov_b32 s18, 0
	s_mov_b32 s28, 2

; __device__ __forceinline__ unsigned pack2(float lo, float hi) { unsigned r; asm("v_cvt_pk_bf16_f32 %0, %1, %2" : "=v"(r) : "v"(lo), "v"(hi)); return r; }
; __device__ __forceinline__ void convert_weight(int wv, const float* __restrict__ src, int ldsrc, int Ksrc, bf16_t* dst, int ldd, int koff, int ntn, const float* kscale, int mode, LAS float* tile, int pidx, int pcnt) {
;     ...
;         const int tn = t % ntn, tk = t / ntn; const int n0 = tn * 64, k0 = tk * 128;
;         if (t + G < total) prefetch(t + G);
;         { const int n = tid >> 3, k16 = (tid & 7) * 16; u32x4 w0, w1;
;           w0.x = pack2(tl[(k16 + 0) * 65 + n], tl[(k16 + 1) * 65 + n]); w0.y = pack2(tl[(k16 + 2) * 65 + n], tl[(k16 + 3) * 65 + n]);
;           w0.z = pack2(tl[(k16 + 4) * 65 + n], tl[(k16 + 5) * 65 + n]); w0.w = pack2(tl[(k16 + 6) * 65 + n], tl[(k16 + 7) * 65 + n]);
;           w1.x = pack2(tl[(k16 + 8) * 65 + n], tl[(k16 + 9) * 65 + n]); w1.y = pack2(tl[(k16 + 10) * 65 + n], tl[(k16 + 11) * 65 + n]);
;           w1.z = pack2(tl[(k16 + 12) * 65 + n], tl[(k16 + 13) * 65 + n]); w1.w = pack2(tl[(k16 + 14) * 65 + n], tl[(k16 + 15) * 65 + n]);
;           bf16_t* dp = dst + (size_t)(n0 + n) * ldd + koff + k0 + k16; *(u32x4*)dp = w0; *(u32x4*)(dp + 8) = w1; }
;         buf ^= 1;
.Lcv1_na:
	ds_read_b32 v52, v7 offset:0
	ds_read_b32 v53, v7 offset:260
	ds_read_b32 v54, v7 offset:520
	ds_read_b32 v55, v7 offset:780
	ds_read_b32 v56, v7 offset:1040
	ds_read_b32 v57, v7 offset:1300
	ds_read_b32 v58, v7 offset:1560
	ds_read_b32 v59, v7 offset:1820
	ds_read_b32 v60, v7 offset:2080
	ds_read_b32 v61, v7 offset:2340
	ds_read_b32 v62, v7 offset:2600
	ds_read_b32 v63, v7 offset:2860
	ds_read_b32 v64, v7 offset:3120
	ds_read_b32 v65, v7 offset:3380
	ds_read_b32 v66, v7 offset:3640
	ds_read_b32 v67, v7 offset:3900
	s_mul_hi_u32 s15, s10, 0x13521d0
	s_mul_i32 s14, s15, 212
	s_sub_u32 s14, s10, s14
	s_mul_i32 s14, s14, 0x40000
	s_lshl_b32 s15, s15, 8
	s_add_u32 s14, s14, s15
	s_add_u32 s24, s8, s14
	s_addc_u32 s25, s9, 0
	s_waitcnt lgkmcnt(14)
	v_cvt_pk_bf16_f32 v68, v52, v53
	s_waitcnt lgkmcnt(12)
	v_cvt_pk_bf16_f32 v69, v54, v55
	s_waitcnt lgkmcnt(10)
	v_cvt_pk_bf16_f32 v70, v56, v57
	s_waitcnt lgkmcnt(8)
	v_cvt_pk_bf16_f32 v71, v58, v59
	s_waitcnt lgkmcnt(6)
	v_cvt_pk_bf16_f32 v72, v60, v61
	s_waitcnt lgkmcnt(4)
	v_cvt_pk_bf16_f32 v73, v62, v63
	s_waitcnt lgkmcnt(2)
	v_cvt_pk_bf16_f32 v74, v64, v65
	s_waitcnt lgkmcnt(0)
	v_cvt_pk_bf16_f32 v75, v66, v67
	global_store_dwordx4 v8, v[68:71], s[24:25]
	global_store_dwordx4 v8, v[72:75], s[24:25] offset:16
	s_add_u32 s10, s10, 192
	s_cmp_lt_u32 s10, 2462
	s_cbranch_scc0 .Lcv1_end
	s_cmp_eq_u32 s27, 0
	s_cbranch_scc1 .Lcv1_wa
	s_waitcnt vmcnt(10)
	s_branch .Lcv1_xa

; #define LAS __attribute__((address_space(3)))
; __device__ __forceinline__ void lds_barrier() { asm volatile("s_waitcnt lgkmcnt(0)" ::: "memory"); __builtin_amdgcn_s_barrier(); asm volatile("" ::: "memory"); }
; __device__ __forceinline__ void convert_weight(int wv, const float* __restrict__ src, int ldsrc, int Ksrc, bf16_t* dst, int ldd, int koff, int ntn, const float* kscale, int mode, LAS float* tile, int pidx, int pcnt) {
;     ...
;         for (int i = 0; i < 4; ++i) { const int kk = kk0 + i * 32; v[i] = (f32x4){0.f, 0.f, 0.f, 0.f};
;             if (n4 < nvalid) v[i] = *(const f32x4*)(src + (size_t)(k0 + kk) * ldsrc + scol + n4);
;             ks[i] = kscale ? kscale[k0 + kk] : 1.0f; }
;     };
;     int t = pidx; int buf = 0;
;     if (t < total) prefetch(t);
;     for (; t < total; t += G) {
;         LAS float* tl = tile + buf * (128 * 65);
; #pragma unroll
;         for (int i = 0; i < 4; ++i) { const int kk = kk0 + i * 32;
;             tl[kk * 65 + n4 + 0] = v[i][0] * ks[i]; tl[kk * 65 + n4 + 1] = v[i][1] * ks[i]; tl[kk * 65 + n4 + 2] = v[i][2] * ks[i]; tl[kk * 65 + n4 + 3] = v[i][3] * ks[i]; }
;         lds_barrier();
;         const int tn = t % ntn, tk = t / ntn; const int n0 = tn * 64, k0 = tk * 128;
;         if (t + G < total) prefetch(t + G);
.Lcv1_mb:
	v_mul_f32_e32 v32, v32, v48
	v_mul_f32_e32 v33, v33, v48
	v_mul_f32_e32 v34, v34, v48
	v_mul_f32_e32 v35, v35, v48
	v_mul_f32_e32 v36, v36, v49
	v_mul_f32_e32 v37, v37, v49
	v_mul_f32_e32 v38, v38, v49
	v_mul_f32_e32 v39, v39, v49
	v_mul_f32_e32 v40, v40, v50
	v_mul_f32_e32 v41, v41, v50
	v_mul_f32_e32 v42, v42, v50
	v_mul_f32_e32 v43, v43, v50
	v_mul_f32_e32 v44, v44, v51
	v_mul_f32_e32 v45, v45, v51
	v_mul_f32_e32 v46, v46, v51
	v_mul_f32_e32 v47, v47, v51
	ds_write_b32 v6, v32 offset:33280
	ds_write_b32 v6, v33 offset:33284
	ds_write_b32 v6, v34 offset:33288
	ds_write_b32 v6, v35 offset:33292
	ds_write_b32 v6, v36 offset:41600
	ds_write_b32 v6, v37 offset:41604
	ds_write_b32 v6, v38 offset:41608
	ds_write_b32 v6, v39 offset:41612
	ds_write_b32 v6, v40 offset:49920
	ds_write_b32 v6, v41 offset:49924
	ds_write_b32 v6, v42 offset:49928
	ds_write_b32 v6, v43 offset:49932
	ds_write_b32 v6, v44 offset:58240
	ds_write_b32 v6, v45 offset:58244
	ds_write_b32 v6, v46 offset:58248
	ds_write_b32 v6, v47 offset:58252
	s_waitcnt lgkmcnt(0)
	s_barrier
	s_add_u32 s11, s10, 384
	s_mov_b32 s27, 0
	s_cmp_lt_u32 s11, 2462
	s_cbranch_scc0 .Lcv1_nb
	s_mov_b32 s27, 1
	s_mul_hi_u32 s15, s11, 0x13521d0
	s_mul_i32 s14, s15, 212
	s_sub_u32 s14, s11, s14
	s_lshl_b32 s18, s14, 6
	s_mov_b32 s29, 0
	s_cmp_lt_u32 s14, 88
	s_cbranch_scc1 .Lcv1_cb
	s_add_u32 s18, s18, 8
	s_cmp_lt_u32 s14, 208
	s_cbranch_scc1 .Lcv1_cb
	s_movk_i32 s18, 0x1600
	s_mov_b32 s29, 1
	s_cmp_eq_u32 s14, 208
	s_cbranch_scc1 .Lcv1_cb
	s_mov_b32 s18, 0
	s_mov_b32 s29, 2

; __device__ __forceinline__ unsigned pack2(float lo, float hi) { unsigned r; asm("v_cvt_pk_bf16_f32 %0, %1, %2" : "=v"(r) : "v"(lo), "v"(hi)); return r; }
; __device__ __forceinline__ void convert_weight(int wv, const float* __restrict__ src, int ldsrc, int Ksrc, bf16_t* dst, int ldd, int koff, int ntn, const float* kscale, int mode, LAS float* tile, int pidx, int pcnt) {
;     ...
;         const int tn = t % ntn, tk = t / ntn; const int n0 = tn * 64, k0 = tk * 128;
;         if (t + G < total) prefetch(t + G);
;         { const int n = tid >> 3, k16 = (tid & 7) * 16; u32x4 w0, w1;
;           w0.x = pack2(tl[(k16 + 0) * 65 + n], tl[(k16 + 1) * 65 + n]); w0.y = pack2(tl[(k16 + 2) * 65 + n], tl[(k16 + 3) * 65 + n]);
;           w0.z = pack2(tl[(k16 + 4) * 65 + n], tl[(k16 + 5) * 65 + n]); w0.w = pack2(tl[(k16 + 6) * 65 + n], tl[(k16 + 7) * 65 + n]);
;           w1.x = pack2(tl[(k16 + 8) * 65 + n], tl[(k16 + 9) * 65 + n]); w1.y = pack2(tl[(k16 + 10) * 65 + n], tl[(k16 + 11) * 65 + n]);
;           w1.z = pack2(tl[(k16 + 12) * 65 + n], tl[(k16 + 13) * 65 + n]); w1.w = pack2(tl[(k16 + 14) * 65 + n], tl[(k16 + 15) * 65 + n]);
;           bf16_t* dp = dst + (size_t)(n0 + n) * ldd + koff + k0 + k16; *(u32x4*)dp = w0; *(u32x4*)(dp + 8) = w1; }
;         buf ^= 1;
.Lcv1_nb:
	ds_read_b32 v52, v7 offset:33280
	ds_read_b32 v53, v7 offset:33540
	ds_read_b32 v54, v7 offset:33800
	ds_read_b32 v55, v7 offset:34060
	ds_read_b32 v56, v7 offset:34320
	ds_read_b32 v57, v7 offset:34580
	ds_read_b32 v58, v7 offset:34840
	ds_read_b32 v59, v7 offset:35100
	ds_read_b32 v60, v7 offset:35360
	ds_read_b32 v61, v7 offset:35620
	ds_read_b32 v62, v7 offset:35880
	ds_read_b32 v63, v7 offset:36140
	ds_read_b32 v64, v7 offset:36400
	ds_read_b32 v65, v7 offset:36660
	ds_read_b32 v66, v7 offset:36920
	ds_read_b32 v67, v7 offset:37180
	s_mul_hi_u32 s15, s10, 0x13521d0
	s_mul_i32 s14, s15, 212
	s_sub_u32 s14, s10, s14
	s_mul_i32 s14, s14, 0x40000
	s_lshl_b32 s15, s15, 8
	s_add_u32 s14, s14, s15
	s_add_u32 s24, s8, s14
	s_addc_u32 s25, s9, 0
	s_waitcnt lgkmcnt(14)
	v_cvt_pk_bf16_f32 v68, v52, v53
	s_waitcnt lgkmcnt(12)
	v_cvt_pk_bf16_f32 v69, v54, v55
	s_waitcnt lgkmcnt(10)
	v_cvt_pk_bf16_f32 v70, v56, v57
	s_waitcnt lgkmcnt(8)
	v_cvt_pk_bf16_f32 v71, v58, v59
	s_waitcnt lgkmcnt(6)
	v_cvt_pk_bf16_f32 v72, v60, v61
	s_waitcnt lgkmcnt(4)
	v_cvt_pk_bf16_f32 v73, v62, v63
	s_waitcnt lgkmcnt(2)
	v_cvt_pk_bf16_f32 v74, v64, v65
	s_waitcnt lgkmcnt(0)
	v_cvt_pk_bf16_f32 v75, v66, v67
	global_store_dwordx4 v8, v[68:71], s[24:25]
	global_store_dwordx4 v8, v[72:75], s[24:25] offset:16
	s_add_u32 s10, s10, 192
	s_cmp_lt_u32 s10, 2462
	s_cbranch_scc0 .Lcv1_end
	s_cmp_eq_u32 s27, 0
	s_cbranch_scc1 .Lcv1_wb
	s_waitcnt vmcnt(10)
	s_branch .Lcv1_xb

; #define LAS __attribute__((address_space(3)))
; __device__ __forceinline__ PP get_params() { unsigned long long kp = (unsigned long long)__builtin_amdgcn_kernarg_segment_ptr(); asm volatile("" : "+s"(kp)); return (PP)kp; }
; __device__ __forceinline__ int opaque_tid(int wv) { asm volatile("" : "+s"(wv)); unsigned z = 0u; asm volatile("" : "+v"(z)); const int l = __builtin_amdgcn_mbcnt_hi(~0u, __builtin_amdgcn_mbcnt_lo(~0u, z)); return (wv << 6) | l; }
; __device__ __forceinline__ int opaque_bid() { int t = blockIdx.x; asm volatile("" : "+s"(t)); return t; }
; __device__ __forceinline__ void convert_weight(int wv, const float* __restrict__ src, int ldsrc, int Ksrc, bf16_t* dst, int ldd, int koff, int ntn, const float* kscale, int mode, LAS float* tile, int pidx, int pcnt) {
;     const int tid = opaque_tid(wv); const int ntk = Ksrc / 128; const int total = ntn * ntk; const int G = pcnt;
;     const int kk0 = tid >> 4, n4 = (tid & 15) * 4;
;     f32x4 v[4]; float ks[4];
;     auto prefetch = [&](int t) {
;         const int tn = t % ntn, tk = t / ntn; const int n0 = tn * 64, k0 = tk * 128;
;         int scol = n0, nvalid = 64;
;         if (mode == 1) { if (n0 < 5632) scol = n0; else if (n0 < 13312) scol = n0 + 8; else if (n0 == 13312) { scol = 5632; nvalid = 8; } else { scol = 0; nvalid = 0; } }
; #pragma unroll
;         for (int i = 0; i < 4; ++i) { const int kk = kk0 + i * 32; v[i] = (f32x4){0.f, 0.f, 0.f, 0.f};
;             if (n4 < nvalid) v[i] = *(const f32x4*)(src + (size_t)(k0 + kk) * ldsrc + scol + n4);
;             ks[i] = kscale ? kscale[k0 + kk] : 1.0f; }
;     };
;     int t = pidx; int buf = 0;
;     if (t < total) prefetch(t);
; __device__ __forceinline__ void convert_layer(int wv, PP P, int L, int mask, LAS float* tile, int pidx, int pcnt) {
;     ...
;     if (mask & 1) convert_weight(wv, P->w_in + (size_t)L * D * DIN, DIN, D, (bf16_t*)(ws + WS_WIN), D, 0, NZ / 64, P->norm_mix + L * D, 1, tile, pidx, pcnt);
; __device__ __forceinline__ void fill_convert(int wv, LAS unsigned char* lds, int nunits, int L, int mask) {
;     const int G = (int)gridDim.x, extra = nunits % G, bid = opaque_bid();
;     if (extra != 0 && bid >= extra) convert_layer(wv, get_params(), L, mask, (LAS float*)lds, bid - extra, G - extra);
.LBB0_771:
	v_readlane_b32 s4, v254, 30
	v_readlane_b32 s5, v254, 31
	s_and_b64 vcc, exec, s[4:5]
	s_cbranch_vccnz .LBB0_802
	s_cmp_lt_u32 s81, 176
	s_cbranch_scc1 .LBB0_802
	v_mbcnt_lo_u32_b32 v10, -1, 0
	v_mbcnt_hi_u32_b32 v10, -1, v10
	v_lshl_or_b32 v10, s95, 6, v10
	v_lshrrev_b32_e32 v11, 4, v10
	v_and_b32_e32 v9, 15, v10
	v_lshlrev_b32_e32 v9, 2, v9
	v_mul_u32_u24_e32 v4, 0x3408, v11
	v_add_u32_e32 v4, v4, v9
	v_lshlrev_b32_e32 v4, 2, v4
	v_lshlrev_b32_e32 v5, 2, v11
	v_mul_u32_u24_e32 v6, 65, v11
	v_add_u32_e32 v6, v6, v9
	v_lshlrev_b32_e32 v6, 2, v6
	v_lshrrev_b32_e32 v7, 3, v10
	v_and_b32_e32 v8, 7, v10
	v_lshlrev_b32_e32 v8, 4, v8
	v_mul_u32_u24_e32 v11, 65, v8
	v_add_u32_e32 v11, v11, v7
	v_lshlrev_b32_e32 v8, 1, v8
	v_mul_u32_u24_e32 v10, 0x1000, v7
	v_add_u32_e32 v8, v10, v8
	v_lshlrev_b32_e32 v7, 2, v11
	s_load_dwordx2 s[4:5], s[0:1], 0x18
	s_load_dwordx2 s[6:7], s[0:1], 0x10
	s_load_dwordx2 s[8:9], s[0:1], 0xa0
	s_waitcnt lgkmcnt(0)
	s_add_u32 s4, s4, 0x6810000
	s_addc_u32 s5, s5, 0
	s_add_u32 s6, s6, 0x2000
	s_addc_u32 s7, s7, 0
	s_add_u32 s8, s8, 0x23100000
	s_addc_u32 s9, s9, 0
	s_sub_u32 s10, s81, 176
	s_add_u32 s10, s10, 2462
	s_mul_hi_u32 s15, s10, 0x13521d0
	s_mul_i32 s14, s15, 212
	s_sub_u32 s14, s10, s14
	s_lshl_b32 s18, s14, 6
	s_mov_b32 s28, 0
	s_cmp_lt_u32 s14, 88
	s_cbranch_scc1 .Lcv5_cp0
	s_add_u32 s18, s18, 8
	s_cmp_lt_u32 s14, 208
	s_cbranch_scc1 .Lcv5_cp0
	s_movk_i32 s18, 0x1600
	s_mov_b32 s28, 1
	s_cmp_eq_u32 s14, 208
	s_cbranch_scc1 .Lcv5_cp0
	s_mov_b32 s18, 0
	s_mov_b32 s28, 2
.Lcv5_cp0:
	s_mul_i32 s19, s15, 0x1a0400
	s_add_u32 s19, s19, s18
	s_lshl_b32 s19, s19, 2
	s_add_u32 s20, s4, s19
	s_addc_u32 s21, s5, 0
	s_lshl_b32 s19, s15, 9
	s_add_u32 s22, s6, s19
	s_addc_u32 s23, s7, 0
	global_load_dwordx4 v[12:15], v4, s[20:21]
	global_load_dword v28, v5, s[22:23]
	s_add_u32 s20, s20, 0x1a0400
	s_addc_u32 s21, s21, 0
	global_load_dwordx4 v[16:19], v4, s[20:21]
	global_load_dword v29, v5, s[22:23] offset:128
	s_add_u32 s20, s20, 0x1a0400
	s_addc_u32 s21, s21, 0
	global_load_dwordx4 v[20:23], v4, s[20:21]
	global_load_dword v30, v5, s[22:23] offset:256
	s_add_u32 s20, s20, 0x1a0400
	s_addc_u32 s21, s21, 0
	global_load_dwordx4 v[24:27], v4, s[20:21]
	global_load_dword v31, v5, s[22:23] offset:384
	s_add_u32 s11, s10, 80
	s_cmp_lt_u32 s11, 3392
	s_cbranch_scc0 .Lcv5_p1n
	s_mul_hi_u32 s15, s11, 0x13521d0
	s_mul_i32 s14, s15, 212
	s_sub_u32 s14, s11, s14
	s_lshl_b32 s18, s14, 6
	s_mov_b32 s29, 0
	s_cmp_lt_u32 s14, 88
	s_cbranch_scc1 .Lcv5_cp1
	s_add_u32 s18, s18, 8
	s_cmp_lt_u32 s14, 208
	s_cbranch_scc1 .Lcv5_cp1
	s_movk_i32 s18, 0x1600
	s_mov_b32 s29, 1
	s_cmp_eq_u32 s14, 208
	s_cbranch_scc1 .Lcv5_cp1
	s_mov_b32 s18, 0
	s_mov_b32 s29, 2

; #define LAS __attribute__((address_space(3)))
; __device__ __forceinline__ void lds_barrier() { asm volatile("s_waitcnt lgkmcnt(0)" ::: "memory"); __builtin_amdgcn_s_barrier(); asm volatile("" ::: "memory"); }
; __device__ __forceinline__ void convert_weight(int wv, const float* __restrict__ src, int ldsrc, int Ksrc, bf16_t* dst, int ldd, int koff, int ntn, const float* kscale, int mode, LAS float* tile, int pidx, int pcnt) {
;     ...
;         for (int i = 0; i < 4; ++i) { const int kk = kk0 + i * 32; v[i] = (f32x4){0.f, 0.f, 0.f, 0.f};
;             if (n4 < nvalid) v[i] = *(const f32x4*)(src + (size_t)(k0 + kk) * ldsrc + scol + n4);
;             ks[i] = kscale ? kscale[k0 + kk] : 1.0f; }
;     };
;     int t = pidx; int buf = 0;
;     if (t < total) prefetch(t);
;     for (; t < total; t += G) {
;         LAS float* tl = tile + buf * (128 * 65);
; #pragma unroll
;         for (int i = 0; i < 4; ++i) { const int kk = kk0 + i * 32;
;             tl[kk * 65 + n4 + 0] = v[i][0] * ks[i]; tl[kk * 65 + n4 + 1] = v[i][1] * ks[i]; tl[kk * 65 + n4 + 2] = v[i][2] * ks[i]; tl[kk * 65 + n4 + 3] = v[i][3] * ks[i]; }
;         lds_barrier();
;         const int tn = t % ntn, tk = t / ntn; const int n0 = tn * 64, k0 = tk * 128;
;         if (t + G < total) prefetch(t + G);
.Lcv5_ma:
	v_mul_f32_e32 v12, v12, v28
	v_mul_f32_e32 v13, v13, v28
	v_mul_f32_e32 v14, v14, v28
	v_mul_f32_e32 v15, v15, v28
	v_mul_f32_e32 v16, v16, v29
	v_mul_f32_e32 v17, v17, v29
	v_mul_f32_e32 v18, v18, v29
	v_mul_f32_e32 v19, v19, v29
	v_mul_f32_e32 v20, v20, v30
	v_mul_f32_e32 v21, v21, v30
	v_mul_f32_e32 v22, v22, v30
	v_mul_f32_e32 v23, v23, v30
	v_mul_f32_e32 v24, v24, v31
	v_mul_f32_e32 v25, v25, v31
	v_mul_f32_e32 v26, v26, v31
	v_mul_f32_e32 v27, v27, v31
	ds_write_b32 v6, v12 offset:0
	ds_write_b32 v6, v13 offset:4
	ds_write_b32 v6, v14 offset:8
	ds_write_b32 v6, v15 offset:12
	ds_write_b32 v6, v16 offset:8320
	ds_write_b32 v6, v17 offset:8324
	ds_write_b32 v6, v18 offset:8328
	ds_write_b32 v6, v19 offset:8332
	ds_write_b32 v6, v20 offset:16640
	ds_write_b32 v6, v21 offset:16644
	ds_write_b32 v6, v22 offset:16648
	ds_write_b32 v6, v23 offset:16652
	ds_write_b32 v6, v24 offset:24960
	ds_write_b32 v6, v25 offset:24964
	ds_write_b32 v6, v26 offset:24968
	ds_write_b32 v6, v27 offset:24972
	s_waitcnt lgkmcnt(0)
	s_barrier
	s_add_u32 s11, s10, 160
	s_mov_b32 s27, 0
	s_cmp_lt_u32 s11, 3392
	s_cbranch_scc0 .Lcv5_na
	s_mov_b32 s27, 1
	s_mul_hi_u32 s15, s11, 0x13521d0
	s_mul_i32 s14, s15, 212
	s_sub_u32 s14, s11, s14
	s_lshl_b32 s18, s14, 6
	s_mov_b32 s28, 0
	s_cmp_lt_u32 s14, 88
	s_cbranch_scc1 .Lcv5_ca
	s_add_u32 s18, s18, 8
	s_cmp_lt_u32 s14, 208
	s_cbranch_scc1 .Lcv5_ca
	s_movk_i32 s18, 0x1600
	s_mov_b32 s28, 1
	s_cmp_eq_u32 s14, 208
	s_cbranch_scc1 .Lcv5_ca
	s_mov_b32 s18, 0
	s_mov_b32 s28, 2

; __device__ __forceinline__ unsigned pack2(float lo, float hi) { unsigned r; asm("v_cvt_pk_bf16_f32 %0, %1, %2" : "=v"(r) : "v"(lo), "v"(hi)); return r; }
; __device__ __forceinline__ void convert_weight(int wv, const float* __restrict__ src, int ldsrc, int Ksrc, bf16_t* dst, int ldd, int koff, int ntn, const float* kscale, int mode, LAS float* tile, int pidx, int pcnt) {
;     ...
;         const int tn = t % ntn, tk = t / ntn; const int n0 = tn * 64, k0 = tk * 128;
;         if (t + G < total) prefetch(t + G);
;         { const int n = tid >> 3, k16 = (tid & 7) * 16; u32x4 w0, w1;
;           w0.x = pack2(tl[(k16 + 0) * 65 + n], tl[(k16 + 1) * 65 + n]); w0.y = pack2(tl[(k16 + 2) * 65 + n], tl[(k16 + 3) * 65 + n]);
;           w0.z = pack2(tl[(k16 + 4) * 65 + n], tl[(k16 + 5) * 65 + n]); w0.w = pack2(tl[(k16 + 6) * 65 + n], tl[(k16 + 7) * 65 + n]);
;           w1.x = pack2(tl[(k16 + 8) * 65 + n], tl[(k16 + 9) * 65 + n]); w1.y = pack2(tl[(k16 + 10) * 65 + n], tl[(k16 + 11) * 65 + n]);
;           w1.z = pack2(tl[(k16 + 12) * 65 + n], tl[(k16 + 13) * 65 + n]); w1.w = pack2(tl[(k16 + 14) * 65 + n], tl[(k16 + 15) * 65 + n]);
;           bf16_t* dp = dst + (size_t)(n0 + n) * ldd + koff + k0 + k16; *(u32x4*)dp = w0; *(u32x4*)(dp + 8) = w1; }
;         buf ^= 1;
.Lcv5_na:
	ds_read_b32 v52, v7 offset:0
	ds_read_b32 v53, v7 offset:260
	ds_read_b32 v54, v7 offset:520
	ds_read_b32 v55, v7 offset:780
	ds_read_b32 v56, v7 offset:1040
	ds_read_b32 v57, v7 offset:1300
	ds_read_b32 v58, v7 offset:1560
	ds_read_b32 v59, v7 offset:1820
	ds_read_b32 v60, v7 offset:2080
	ds_read_b32 v61, v7 offset:2340
	ds_read_b32 v62, v7 offset:2600
	ds_read_b32 v63, v7 offset:2860
	ds_read_b32 v64, v7 offset:3120
	ds_read_b32 v65, v7 offset:3380
	ds_read_b32 v66, v7 offset:3640
	ds_read_b32 v67, v7 offset:3900
	s_mul_hi_u32 s15, s10, 0x13521d0
	s_mul_i32 s14, s15, 212
	s_sub_u32 s14, s10, s14
	s_mul_i32 s14, s14, 0x40000
	s_lshl_b32 s15, s15, 8
	s_add_u32 s14, s14, s15
	s_add_u32 s24, s8, s14
	s_addc_u32 s25, s9, 0
	s_waitcnt lgkmcnt(14)
	v_cvt_pk_bf16_f32 v68, v52, v53
	s_waitcnt lgkmcnt(12)
	v_cvt_pk_bf16_f32 v69, v54, v55
	s_waitcnt lgkmcnt(10)
	v_cvt_pk_bf16_f32 v70, v56, v57
	s_waitcnt lgkmcnt(8)
	v_cvt_pk_bf16_f32 v71, v58, v59
	s_waitcnt lgkmcnt(6)
	v_cvt_pk_bf16_f32 v72, v60, v61
	s_waitcnt lgkmcnt(4)
	v_cvt_pk_bf16_f32 v73, v62, v63
	s_waitcnt lgkmcnt(2)
	v_cvt_pk_bf16_f32 v74, v64, v65
	s_waitcnt lgkmcnt(0)
	v_cvt_pk_bf16_f32 v75, v66, v67
	global_store_dwordx4 v8, v[68:71], s[24:25]
	global_store_dwordx4 v8, v[72:75], s[24:25] offset:16
	s_add_u32 s10, s10, 80
	s_cmp_lt_u32 s10, 3392
	s_cbranch_scc0 .Lcv5_end
	s_cmp_eq_u32 s27, 0
	s_cbranch_scc1 .Lcv5_wa
	s_waitcnt vmcnt(10)
	s_branch .Lcv5_xa

; #define LAS __attribute__((address_space(3)))
; __device__ __forceinline__ void lds_barrier() { asm volatile("s_waitcnt lgkmcnt(0)" ::: "memory"); __builtin_amdgcn_s_barrier(); asm volatile("" ::: "memory"); }
; __device__ __forceinline__ void convert_weight(int wv, const float* __restrict__ src, int ldsrc, int Ksrc, bf16_t* dst, int ldd, int koff, int ntn, const float* kscale, int mode, LAS float* tile, int pidx, int pcnt) {
;     ...
;         for (int i = 0; i < 4; ++i) { const int kk = kk0 + i * 32; v[i] = (f32x4){0.f, 0.f, 0.f, 0.f};
;             if (n4 < nvalid) v[i] = *(const f32x4*)(src + (size_t)(k0 + kk) * ldsrc + scol + n4);
;             ks[i] = kscale ? kscale[k0 + kk] : 1.0f; }
;     };
;     int t = pidx; int buf = 0;
;     if (t < total) prefetch(t);
;     for (; t < total; t += G) {
;         LAS float* tl = tile + buf * (128 * 65);
; #pragma unroll
;         for (int i = 0; i < 4; ++i) { const int kk = kk0 + i * 32;
;             tl[kk * 65 + n4 + 0] = v[i][0] * ks[i]; tl[kk * 65 + n4 + 1] = v[i][1] * ks[i]; tl[kk * 65 + n4 + 2] = v[i][2] * ks[i]; tl[kk * 65 + n4 + 3] = v[i][3] * ks[i]; }
;         lds_barrier();
;         const int tn = t % ntn, tk = t / ntn; const int n0 = tn * 64, k0 = tk * 128;
;         if (t + G < total) prefetch(t + G);
.Lcv5_mb:
	v_mul_f32_e32 v32, v32, v48
	v_mul_f32_e32 v33, v33, v48
	v_mul_f32_e32 v34, v34, v48
	v_mul_f32_e32 v35, v35, v48
	v_mul_f32_e32 v36, v36, v49
	v_mul_f32_e32 v37, v37, v49
	v_mul_f32_e32 v38, v38, v49
	v_mul_f32_e32 v39, v39, v49
	v_mul_f32_e32 v40, v40, v50
	v_mul_f32_e32 v41, v41, v50
	v_mul_f32_e32 v42, v42, v50
	v_mul_f32_e32 v43, v43, v50
	v_mul_f32_e32 v44, v44, v51
	v_mul_f32_e32 v45, v45, v51
	v_mul_f32_e32 v46, v46, v51
	v_mul_f32_e32 v47, v47, v51
	ds_write_b32 v6, v32 offset:33280
	ds_write_b32 v6, v33 offset:33284
	ds_write_b32 v6, v34 offset:33288
	ds_write_b32 v6, v35 offset:33292
	ds_write_b32 v6, v36 offset:41600
	ds_write_b32 v6, v37 offset:41604
	ds_write_b32 v6, v38 offset:41608
	ds_write_b32 v6, v39 offset:41612
	ds_write_b32 v6, v40 offset:49920
	ds_write_b32 v6, v41 offset:49924
	ds_write_b32 v6, v42 offset:49928
	ds_write_b32 v6, v43 offset:49932
	ds_write_b32 v6, v44 offset:58240
	ds_write_b32 v6, v45 offset:58244
	ds_write_b32 v6, v46 offset:58248
	ds_write_b32 v6, v47 offset:58252
	s_waitcnt lgkmcnt(0)
	s_barrier
	s_add_u32 s11, s10, 160
	s_mov_b32 s27, 0
	s_cmp_lt_u32 s11, 3392
	s_cbranch_scc0 .Lcv5_nb
	s_mov_b32 s27, 1
	s_mul_hi_u32 s15, s11, 0x13521d0
	s_mul_i32 s14, s15, 212
	s_sub_u32 s14, s11, s14
	s_lshl_b32 s18, s14, 6
	s_mov_b32 s29, 0
	s_cmp_lt_u32 s14, 88
	s_cbranch_scc1 .Lcv5_cb
	s_add_u32 s18, s18, 8
	s_cmp_lt_u32 s14, 208
	s_cbranch_scc1 .Lcv5_cb
	s_movk_i32 s18, 0x1600
	s_mov_b32 s29, 1
	s_cmp_eq_u32 s14, 208
	s_cbranch_scc1 .Lcv5_cb
	s_mov_b32 s18, 0
	s_mov_b32 s29, 2

; __device__ __forceinline__ unsigned pack2(float lo, float hi) { unsigned r; asm("v_cvt_pk_bf16_f32 %0, %1, %2" : "=v"(r) : "v"(lo), "v"(hi)); return r; }
; __device__ __forceinline__ void convert_weight(int wv, const float* __restrict__ src, int ldsrc, int Ksrc, bf16_t* dst, int ldd, int koff, int ntn, const float* kscale, int mode, LAS float* tile, int pidx, int pcnt) {
;     ...
;         const int tn = t % ntn, tk = t / ntn; const int n0 = tn * 64, k0 = tk * 128;
;         if (t + G < total) prefetch(t + G);
;         { const int n = tid >> 3, k16 = (tid & 7) * 16; u32x4 w0, w1;
;           w0.x = pack2(tl[(k16 + 0) * 65 + n], tl[(k16 + 1) * 65 + n]); w0.y = pack2(tl[(k16 + 2) * 65 + n], tl[(k16 + 3) * 65 + n]);
;           w0.z = pack2(tl[(k16 + 4) * 65 + n], tl[(k16 + 5) * 65 + n]); w0.w = pack2(tl[(k16 + 6) * 65 + n], tl[(k16 + 7) * 65 + n]);
;           w1.x = pack2(tl[(k16 + 8) * 65 + n], tl[(k16 + 9) * 65 + n]); w1.y = pack2(tl[(k16 + 10) * 65 + n], tl[(k16 + 11) * 65 + n]);
;           w1.z = pack2(tl[(k16 + 12) * 65 + n], tl[(k16 + 13) * 65 + n]); w1.w = pack2(tl[(k16 + 14) * 65 + n], tl[(k16 + 15) * 65 + n]);
;           bf16_t* dp = dst + (size_t)(n0 + n) * ldd + koff + k0 + k16; *(u32x4*)dp = w0; *(u32x4*)(dp + 8) = w1; }
;         buf ^= 1;
.Lcv5_nb:
	ds_read_b32 v52, v7 offset:33280
	ds_read_b32 v53, v7 offset:33540
	ds_read_b32 v54, v7 offset:33800
	ds_read_b32 v55, v7 offset:34060
	ds_read_b32 v56, v7 offset:34320
	ds_read_b32 v57, v7 offset:34580
	ds_read_b32 v58, v7 offset:34840
	ds_read_b32 v59, v7 offset:35100
	ds_read_b32 v60, v7 offset:35360
	ds_read_b32 v61, v7 offset:35620
	ds_read_b32 v62, v7 offset:35880
	ds_read_b32 v63, v7 offset:36140
	ds_read_b32 v64, v7 offset:36400
	ds_read_b32 v65, v7 offset:36660
	ds_read_b32 v66, v7 offset:36920
	ds_read_b32 v67, v7 offset:37180
	s_mul_hi_u32 s15, s10, 0x13521d0
	s_mul_i32 s14, s15, 212
	s_sub_u32 s14, s10, s14
	s_mul_i32 s14, s14, 0x40000
	s_lshl_b32 s15, s15, 8
	s_add_u32 s14, s14, s15
	s_add_u32 s24, s8, s14
	s_addc_u32 s25, s9, 0
	s_waitcnt lgkmcnt(14)
	v_cvt_pk_bf16_f32 v68, v52, v53
	s_waitcnt lgkmcnt(12)
	v_cvt_pk_bf16_f32 v69, v54, v55
	s_waitcnt lgkmcnt(10)
	v_cvt_pk_bf16_f32 v70, v56, v57
	s_waitcnt lgkmcnt(8)
	v_cvt_pk_bf16_f32 v71, v58, v59
	s_waitcnt lgkmcnt(6)
	v_cvt_pk_bf16_f32 v72, v60, v61
	s_waitcnt lgkmcnt(4)
	v_cvt_pk_bf16_f32 v73, v62, v63
	s_waitcnt lgkmcnt(2)
	v_cvt_pk_bf16_f32 v74, v64, v65
	s_waitcnt lgkmcnt(0)
	v_cvt_pk_bf16_f32 v75, v66, v67
	global_store_dwordx4 v8, v[68:71], s[24:25]
	global_store_dwordx4 v8, v[72:75], s[24:25] offset:16
	s_add_u32 s10, s10, 80
	s_cmp_lt_u32 s10, 3392
	s_cbranch_scc0 .Lcv5_end
	s_cmp_eq_u32 s27, 0
	s_cbranch_scc1 .Lcv5_wb
	s_waitcnt vmcnt(10)
	s_branch .Lcv5_xb

; #define LAS __attribute__((address_space(3)))
; __device__ __forceinline__ PP get_params() { unsigned long long kp = (unsigned long long)__builtin_amdgcn_kernarg_segment_ptr(); asm volatile("" : "+s"(kp)); return (PP)kp; }
; __device__ __forceinline__ int opaque_tid(int wv) { asm volatile("" : "+s"(wv)); unsigned z = 0u; asm volatile("" : "+v"(z)); const int l = __builtin_amdgcn_mbcnt_hi(~0u, __builtin_amdgcn_mbcnt_lo(~0u, z)); return (wv << 6) | l; }
; __device__ __forceinline__ unsigned xb_add(unsigned* p, unsigned v) { return __hip_atomic_fetch_add(p, v, __ATOMIC_RELAXED, __HIP_MEMORY_SCOPE_AGENT); }
; __device__ __forceinline__ unsigned xb_xcc_id() { return (unsigned)__builtin_amdgcn_s_getreg((3 << 11) | 20) & 0xFu; }
; __device__ __forceinline__ void convert_weight(int wv, const float* __restrict__ src, int ldsrc, int Ksrc, bf16_t* dst, int ldd, int koff, int ntn, const float* kscale, int mode, LAS float* tile, int pidx, int pcnt) {
;     ...
;         buf ^= 1;
;     }
;     __syncthreads();
; __device__ __forceinline__ void gbar(int wv, LAS unsigned char* lds) {
;     asm volatile("s_waitcnt vmcnt(0)" ::: "memory");
;     __syncthreads();
;     const int tid = opaque_tid(wv); unsigned* bar = (unsigned*)(get_params()->ws + WS_BAR);
;     if (tid == 0) {
;         volatile LAS unsigned* st = (volatile LAS unsigned*)(lds + LDS_ST); const unsigned x = xb_xcc_id();
;         __builtin_amdgcn_s_waitcnt(0);
;         unsigned nloc = st[0], nx = st[1];
;         if (nloc == 0u) { xcd_barrier_complete(bar, x, nloc, nx); st[0] = nloc; st[1] = nx; }
;         const unsigned old = xb_add(&bar[XB_XSUB(x)], 1u);
.Lcv5_xb:
	s_branch .Lcv5_loop
.Lcv5_end:
	s_waitcnt lgkmcnt(0)
	s_barrier
.LBB0_802:
	s_mov_b32 s4, s95
	v_mov_b32_e32 v0, v3
	s_waitcnt vmcnt(0)
	s_waitcnt vmcnt(0)
	s_barrier
	s_mov_b64 s[6:7], s[0:1]
	v_mbcnt_lo_u32_b32 v0, -1, v0
	v_mbcnt_hi_u32_b32 v0, -1, v0
	v_lshl_or_b32 v0, s4, 6, v0
	v_cmp_eq_u32_e32 vcc, 0, v0
	s_and_saveexec_b64 s[4:5], vcc
	s_cbranch_execz .LBB0_854
	v_mov_b32_e32 v0, s88
	s_load_dwordx2 s[6:7], s[6:7], 0xa0
	s_getreg_b32 s8, hwreg(HW_REG_XCC_ID, 0, 4)
	s_waitcnt vmcnt(0) expcnt(0) lgkmcnt(0)
	ds_read_b32 v2, v0
	v_mov_b32_e32 v0, s89
	ds_read_b32 v0, v0
	s_and_b32 s46, s8, 15
	s_waitcnt lgkmcnt(1)
	v_cmp_ne_u32_e32 vcc, 0, v2
	s_cbranch_vccnz .LBB0_818
	s_add_u32 s8, s6, 0x285daa00
	s_addc_u32 s9, s7, 0
	s_add_u32 s10, s6, 0x285dac00
	s_addc_u32 s11, s7, 0
	s_add_u32 s12, s6, 0x285dad00
	s_addc_u32 s13, s7, 0
	s_add_u32 s14, s6, 0x285dae00
	s_addc_u32 s15, s7, 0
	s_add_u32 s16, s6, 0x285daf00
	s_addc_u32 s17, s7, 0
	s_add_u32 s18, s6, 0x285db000
	s_addc_u32 s19, s7, 0
	s_add_u32 s20, s6, 0x285db100
	s_addc_u32 s21, s7, 0
	s_add_u32 s22, s6, 0x285db200
	s_addc_u32 s23, s7, 0
	s_add_u32 s24, s6, 0x285db300
	s_addc_u32 s25, s7, 0
	s_add_u32 s26, s6, 0x285db400
	s_addc_u32 s27, s7, 0
	s_add_u32 s28, s6, 0x285db500
	s_addc_u32 s29, s7, 0
	s_add_u32 s30, s6, 0x285db600
	s_addc_u32 s31, s7, 0
	s_add_u32 s34, s6, 0x285db700
	s_addc_u32 s35, s7, 0
	s_add_u32 s36, s6, 0x285db800
	s_addc_u32 s37, s7, 0
	s_add_u32 s38, s6, 0x285db900
	s_addc_u32 s39, s7, 0
	s_add_u32 s40, s6, 0x285dba00
	s_addc_u32 s41, s7, 0
	s_add_u32 s42, s6, 0x285dbb00
	s_addc_u32 s43, s7, 0
	s_mov_b32 s47, 1
	s_branch .LBB0_806
